# adds: epilogue rst barrier no longer drains vmcnt (next-tile stage loads stay in flight through the epilogue, as they already do for the residual / P-store epilogues)
# baseline (speedup 1.0000x reference)
; __device__ __forceinline__ int opaque_tid() { int t = threadIdx.x; asm volatile("" : "+v"(t)); return t; }
;     __device__ __forceinline__ void operator()(AccRef acc, const pg8::Unit& u, int wr, int wc, int fr, int fq) const {
;     ...
;         if (kind == 0 || kind == 2 || kind == 4) {
;             const int t = opaque_tid();
;             if (t < 256) rst[t] = row_rs(rss_in, u.pm * 256 + t);
;             __syncthreads();
;         }
;         if (kind == 0) { EpiSwiglu E{(bf16*)big, rst}; E(acc, u, wr, wc, fr, fq); }
;         else if (kind == 1) { EpiResid E{(bf16*)(ws + WS_HN), outf, scale, rss_out}; E(acc, u, wr, wc, fr, fq); }
;         else if (kind == 2) {
;             const int l = layer;
;             EpiQKV E{big, pp->in[9] + l * 64, pp->in[10] + l * 64, pp->in[13] + l * 64, pp->in[14] + l * 64, pp->in[15] + l * 64, pp->in[16] + l * 64, pp->in[8] + l * 6, (float*)(ws + WS_LOGF), rst};
;             E(acc, u, wr, wc, fr, fq);
;         }
;         else if (kind == 3) { EpiPStore E{(v4u*)(big + B_P)}; E(acc, u, wr, wc, fr, fq); }
;         else { EpiGate E{pp->in[7] + (size_t)layer * 4 * D + (size_t)bi * D, (const v4u*)(big + B_P), (v4u*)(big + B_TMP), (bf16*)(big + B_MRG), bi == 0, bi == 3, rst}; E(acc, u, wr, wc, fr, fq); }
.LBB0_178:
	s_or_b64 exec, exec, s[6:7]
	s_mov_b64 s[18:19], -1
	s_mov_b64 s[96:97], 0
	s_cmp_lt_i32 s15, 2
	s_mov_b64 s[6:7], 0
	s_mov_b64 s[10:11], 0
	s_waitcnt lgkmcnt(0)
	s_barrier
	s_cbranch_scc1 .LBB0_181
	s_mov_b64 s[6:7], -1
	s_mov_b64 s[18:19], 0
	s_cmp_gt_i32 s15, 2
	s_cbranch_scc0 .LBB0_181
	s_cmp_eq_u32 s15, 3
	s_mov_b64 s[6:7], 0
	s_mov_b64 s[8:9], -1
	s_cselect_b64 s[10:11], -1, 0
